# nont_p2
# baseline (speedup 1.0000x reference)
; __device__ __forceinline__ unsigned cvt_pk_bf16(float lo, float hi) { unsigned r; asm volatile("v_cvt_pk_bf16_f32 %0, %1, %2" : "=v"(r) : "v"(lo), "v"(hi)); return r; }
;     __device__ __forceinline__ void operator()(const f32x4 (&acc)[2][2][4][2], const Unit& u, int wr, int wc, int fr, int fq) const {
;     ...
; #pragma unroll
;         for (int ai = 0; ai < 2; ++ai)
; #pragma unroll
;             for (int m = 0; m < 4; ++m) { bf16_t* rowp = base + (size_t)(ai * HALF + m * 16) * rstride;
; #pragma unroll
;                 for (int bj = 0; bj < 2; ++bj) { const f32x4 v0 = acc[ai][bj][m][0], v1 = acc[ai][bj][m][1];
;                     u32x4 w; w.x = cvt_pk_bf16(v0[0], v0[1]); w.y = cvt_pk_bf16(v0[2], v0[3]); w.z = cvt_pk_bf16(v1[0], v1[1]); w.w = cvt_pk_bf16(v1[2], v1[3]);
;                     __builtin_nontemporal_store(w, (u32x4*)(rowp + bj * bjstride)); } }
.LBB0_182:
	v_lshl_add_u64 v[150:151], v[150:151], 0, s[8:9]
	v_lshl_add_u64 v[150:151], v[150:151], 0, v[142:143]
	s_lshl_b32 s26, s26, 1
	s_mov_b32 s27, s9
	v_cvt_pk_bf16_f32 v124, v124, v125
	v_cvt_pk_bf16_f32 v125, v126, v127
	v_cvt_pk_bf16_f32 v126, v120, v121
	v_cvt_pk_bf16_f32 v127, v122, v123
	global_store_dwordx4 v[150:151], v[124:127], off
	v_cvt_pk_bf16_f32 v116, v116, v117
	v_cvt_pk_bf16_f32 v117, v118, v119
	v_cvt_pk_bf16_f32 v118, v108, v109
	v_lshl_add_u64 v[108:109], v[150:151], 0, s[26:27]
	s_lshl_b32 s28, s36, 5
	s_mov_b32 s29, s9
	v_cvt_pk_bf16_f32 v119, v110, v111
	global_store_dwordx4 v[108:109], v[116:119], off
	v_cvt_pk_bf16_f32 v108, v112, v113
	v_cvt_pk_bf16_f32 v109, v114, v115
	v_cvt_pk_bf16_f32 v110, v104, v105
	v_cvt_pk_bf16_f32 v111, v106, v107
	s_mulk_i32 s36, 0xa0
	s_nop 0
	v_lshl_add_u64 v[116:117], v[150:151], 0, s[28:29]
	global_store_dwordx4 v[116:117], v[108:111], off
	v_cvt_pk_bf16_f32 v96, v96, v97
	v_cvt_pk_bf16_f32 v97, v98, v99
	v_cvt_pk_bf16_f32 v98, v88, v89
	v_lshl_add_u64 v[88:89], v[116:117], 0, s[26:27]
	v_cvt_pk_bf16_f32 v99, v90, v91
	global_store_dwordx4 v[88:89], v[96:99], off
	v_cvt_pk_bf16_f32 v88, v100, v101
	v_cvt_pk_bf16_f32 v89, v102, v103
	v_cvt_pk_bf16_f32 v90, v92, v93
	v_cvt_pk_bf16_f32 v91, v94, v95
	s_mov_b32 s37, s9
	s_nop 0
	v_lshl_add_u64 v[96:97], v[116:117], 0, s[28:29]
	global_store_dwordx4 v[96:97], v[88:91], off
	v_cvt_pk_bf16_f32 v80, v80, v81
	v_cvt_pk_bf16_f32 v81, v82, v83
	v_cvt_pk_bf16_f32 v82, v72, v73
	v_lshl_add_u64 v[72:73], v[96:97], 0, s[26:27]
	v_cvt_pk_bf16_f32 v83, v74, v75
	global_store_dwordx4 v[72:73], v[80:83], off
	v_cvt_pk_bf16_f32 v72, v84, v85
	v_cvt_pk_bf16_f32 v73, v86, v87
	v_cvt_pk_bf16_f32 v74, v76, v77
	v_cvt_pk_bf16_f32 v75, v78, v79
	s_and_b64 vcc, exec, s[0:1]
	s_nop 0
	v_lshl_add_u64 v[80:81], v[96:97], 0, s[28:29]
	global_store_dwordx4 v[80:81], v[72:75], off
	v_cvt_pk_bf16_f32 v68, v68, v69
	v_cvt_pk_bf16_f32 v69, v70, v71
	v_cvt_pk_bf16_f32 v70, v64, v65
	v_lshl_add_u64 v[64:65], v[80:81], 0, s[26:27]
	v_cvt_pk_bf16_f32 v71, v66, v67
	global_store_dwordx4 v[64:65], v[68:71], off
	v_lshl_add_u64 v[64:65], v[80:81], 0, s[36:37]
	v_cvt_pk_bf16_f32 v60, v60, v61
	v_cvt_pk_bf16_f32 v61, v62, v63
	v_cvt_pk_bf16_f32 v62, v56, v57
	v_cvt_pk_bf16_f32 v63, v58, v59
	global_store_dwordx4 v[64:65], v[60:63], off
	v_cvt_pk_bf16_f32 v48, v48, v49
	v_cvt_pk_bf16_f32 v49, v50, v51
	v_cvt_pk_bf16_f32 v50, v40, v41
	v_lshl_add_u64 v[40:41], v[64:65], 0, s[26:27]
	v_cvt_pk_bf16_f32 v51, v42, v43
	global_store_dwordx4 v[40:41], v[48:51], off
	v_cvt_pk_bf16_f32 v40, v52, v53
	v_cvt_pk_bf16_f32 v41, v54, v55
	v_cvt_pk_bf16_f32 v42, v44, v45
	v_cvt_pk_bf16_f32 v43, v46, v47
	s_mov_b32 s66, s65
	s_nop 0
	v_lshl_add_u64 v[48:49], v[64:65], 0, s[28:29]
	global_store_dwordx4 v[48:49], v[40:43], off
	v_cvt_pk_bf16_f32 v32, v32, v33
	v_cvt_pk_bf16_f32 v33, v34, v35
	v_cvt_pk_bf16_f32 v34, v24, v25
	v_lshl_add_u64 v[24:25], v[48:49], 0, s[26:27]
	v_cvt_pk_bf16_f32 v35, v26, v27
	global_store_dwordx4 v[24:25], v[32:35], off
	v_cvt_pk_bf16_f32 v24, v36, v37
	v_cvt_pk_bf16_f32 v25, v38, v39
	v_cvt_pk_bf16_f32 v26, v28, v29
	v_cvt_pk_bf16_f32 v27, v30, v31
	s_mov_b64 s[36:37], s[24:25]
	s_nop 0
	v_lshl_add_u64 v[32:33], v[48:49], 0, s[28:29]
	global_store_dwordx4 v[32:33], v[24:27], off
	v_cvt_pk_bf16_f32 v16, v16, v17
	v_cvt_pk_bf16_f32 v17, v18, v19
	v_cvt_pk_bf16_f32 v18, v8, v9
	v_lshl_add_u64 v[8:9], v[32:33], 0, s[26:27]
	v_cvt_pk_bf16_f32 v19, v10, v11
	global_store_dwordx4 v[8:9], v[16:19], off
	v_cvt_pk_bf16_f32 v8, v20, v21
	v_cvt_pk_bf16_f32 v9, v22, v23
	v_cvt_pk_bf16_f32 v10, v12, v13
	v_cvt_pk_bf16_f32 v11, v14, v15
	s_nop 1
	v_lshl_add_u64 v[16:17], v[32:33], 0, s[28:29]
	global_store_dwordx4 v[16:17], v[8:11], off
	v_cvt_pk_bf16_f32 v4, v4, v5
	v_cvt_pk_bf16_f32 v5, v6, v7
	v_cvt_pk_bf16_f32 v6, v0, v1
	v_lshl_add_u64 v[0:1], v[16:17], 0, s[26:27]
	s_mov_b32 s26, s64
	s_mov_b64 s[28:29], s[22:23]
	v_cvt_pk_bf16_f32 v7, v2, v3
	global_store_dwordx4 v[0:1], v[4:7], off
	s_cbranch_vccnz .LBB0_191
